# hg_scan: next-chunk intra-chunk-output loads issued in the LDS-latency shadows of the first MFMA chain; dead zero fill removed
# speedup vs baseline: 1.0012x; 1.0002x over previous
; #define MFMA(a, b, c) __builtin_amdgcn_mfma_f32_32x32x16_bf16((a), (b), (c), 0, 0, 0)
; DI int crow(int r, int h) { return (r & 3) + 8 * (r >> 2) + 4 * h; }
; DI f32x16 zero16() { f32x16 z; for (int i = 0; i < 16; ++i) z[i] = 0.f; return z; }
; DI void stream_of(int n, int cpc, int& m, int& T, int& soff) { if (n < cpc) { m = n; T = CTX; soff = 0; } else { m = n - cpc; T = SEQ; soff = CTX; } }
; DI void hg_scan_block(const Params& p, int chain_in, unsigned char* smem) {
;     ...
;     if (n + 1 < 136) {
;       int m1_, T1_, so1_; stream_of(n + 1, 8, m1_, T1_, so1_);
; #pragma unroll
;       for (int r = 0; r < 16; ++r) {
;         const int pos = 32 * m1_ + crow(r, h), t = dir ? T1_ - 1 - pos : pos;
;         on[r] = OHG[(size_t)(b * SP + so1_ + t) * 512 + hd * 128 + 32 * sl + l31];
;       }
;     } else {
; #pragma unroll
;       for (int r = 0; r < 16; ++r) on[r] = 0.f;
;     }
;     int m, T, soff; stream_of(n, 8, m, T, soff);
;     f32x16 o = zero16();
; #pragma unroll
;     for (int k = 0; k < 4; ++k) {
;       o = MFMA(ld16(s_qhat + ((k * 2 + 0) * 64 + lane) * 8), pack8<0>(S[k]), o);
;       o = MFMA(ld16(s_qhat + ((k * 2 + 1) * 64 + lane) * 8), pack8<1>(S[k]), o);
;     }
.LBB0_497:
	ds_read_b128 v[64:67], v113
	ds_read_b128 v[150:153], v113 offset:1024
	v_cvt_pk_bf16_f32 v68, v48, v49
	v_cvt_pk_bf16_f32 v69, v50, v51
	v_cvt_pk_bf16_f32 v70, v52, v53
	v_cvt_pk_bf16_f32 v71, v54, v55
	v_cvt_pk_bf16_f32 v154, v56, v57
	v_cvt_pk_bf16_f32 v155, v58, v59
	v_cvt_pk_bf16_f32 v156, v60, v61
	s_waitcnt lgkmcnt(0)
	v_mfma_f32_32x32x16_bf16 v[64:79], v[64:67], v[68:71], 0
	v_cvt_pk_bf16_f32 v157, v62, v63
	s_cmp_lt_u32 s21, 8
	s_cselect_b32 s11, 0, -8
	s_cselect_b32 s10, 0x100, s95
	s_cselect_b32 s22, 0, 0x100
	s_add_i32 s11, s11, s21
	s_lshl_b32 s11, s11, 5
	v_mfma_f32_32x32x16_bf16 v[64:79], v[150:153], v[154:157], v[64:79]
	ds_read_b128 v[150:153], v113 offset:2048
	v_mad_i32_i24 v162, v161, 0, v160
	global_load_dword v117, v162, s[36:37]
	v_mad_i32_i24 v163, v161, 1, v160
	global_load_dword v118, v163, s[36:37]
	v_mad_i32_i24 v164, v161, 2, v160
	global_load_dword v119, v164, s[36:37]
	v_cvt_pk_bf16_f32 v154, v32, v33
	v_cvt_pk_bf16_f32 v155, v34, v35
	v_cvt_pk_bf16_f32 v156, v36, v37
	v_cvt_pk_bf16_f32 v157, v38, v39
	s_add_i32 s22, s22, s20
	s_add_i32 s26, s22, s11
	s_sub_i32 s27, s10, s11
	s_add_i32 s27, s27, s22
	s_sub_i32 s27, s27, 32
	s_cmp_lg_u64 s[6:7], 0
	s_cselect_b32 s26, s26, s27
	s_lshl_b32 s26, s26, 11
	s_add_u32 s34, s30, s26
	s_addc_u32 s35, s31, 0
	s_add_u32 s8, s8, 0x6000
	s_addc_u32 s9, s9, 0
	s_waitcnt lgkmcnt(0)
	v_mfma_f32_32x32x16_bf16 v[64:79], v[150:153], v[154:157], v[64:79]
	ds_read_b128 v[150:153], v113 offset:3072
	v_mad_i32_i24 v165, v161, 3, v160
	global_load_dword v120, v165, s[36:37]
	v_mad_i32_i24 v162, v161, 8, v160
	global_load_dword v121, v162, s[36:37]
	v_mad_i32_i24 v163, v161, 9, v160
	global_load_dword v122, v163, s[36:37]
	v_cvt_pk_bf16_f32 v154, v40, v41
	v_cvt_pk_bf16_f32 v155, v42, v43
	v_cvt_pk_bf16_f32 v156, v44, v45
	v_cvt_pk_bf16_f32 v157, v46, v47
	s_add_i32 s21, s21, 1
	s_cmp_lg_u32 s8, 0x330000
	s_waitcnt lgkmcnt(0)
	v_mfma_f32_32x32x16_bf16 v[64:79], v[150:153], v[154:157], v[64:79]
	ds_read_b128 v[150:153], v113 offset:4096
	v_mad_i32_i24 v164, v161, 10, v160
	global_load_dword v123, v164, s[36:37]
	v_mad_i32_i24 v165, v161, 11, v160
	global_load_dword v124, v165, s[36:37]
	v_mad_i32_i24 v162, v161, 16, v160
	global_load_dword v125, v162, s[36:37]
	v_cvt_pk_bf16_f32 v154, v16, v17
	v_cvt_pk_bf16_f32 v155, v18, v19
	v_cvt_pk_bf16_f32 v156, v20, v21
	v_cvt_pk_bf16_f32 v157, v22, v23
	s_waitcnt lgkmcnt(0)
	s_nop 0
	v_mfma_f32_32x32x16_bf16 v[64:79], v[150:153], v[154:157], v[64:79]
	ds_read_b128 v[150:153], v113 offset:5120
	v_mad_i32_i24 v163, v161, 17, v160
	global_load_dword v126, v163, s[36:37]
	v_mad_i32_i24 v164, v161, 18, v160
	global_load_dword v127, v164, s[36:37]
	v_mad_i32_i24 v165, v161, 19, v160
	global_load_dword v128, v165, s[36:37]
	v_cvt_pk_bf16_f32 v154, v24, v25
	v_cvt_pk_bf16_f32 v155, v26, v27
	v_cvt_pk_bf16_f32 v156, v28, v29
	v_cvt_pk_bf16_f32 v157, v30, v31
	s_waitcnt lgkmcnt(0)
	s_nop 0
	v_mfma_f32_32x32x16_bf16 v[64:79], v[150:153], v[154:157], v[64:79]
	ds_read_b128 v[150:153], v113 offset:6144
	v_mad_i32_i24 v162, v161, 24, v160
	global_load_dword v129, v162, s[36:37]
	v_mad_i32_i24 v163, v161, 25, v160
	global_load_dword v130, v163, s[36:37]
	v_cvt_pk_bf16_f32 v154, v0, v1
	v_cvt_pk_bf16_f32 v155, v2, v3
	v_cvt_pk_bf16_f32 v156, v4, v5
	v_cvt_pk_bf16_f32 v157, v6, v7
	s_waitcnt lgkmcnt(0)
	s_nop 0
	v_mfma_f32_32x32x16_bf16 v[64:79], v[150:153], v[154:157], v[64:79]
	ds_read_b128 v[150:153], v113 offset:7168
	v_mad_i32_i24 v164, v161, 26, v160
	global_load_dword v131, v164, s[36:37]
	v_mad_i32_i24 v165, v161, 27, v160
	global_load_dword v134, v165, s[36:37]
	v_cvt_pk_bf16_f32 v154, v8, v9
	v_cvt_pk_bf16_f32 v155, v10, v11
	v_cvt_pk_bf16_f32 v156, v12, v13
	v_cvt_pk_bf16_f32 v157, v14, v15
	s_waitcnt lgkmcnt(0)
; #define MFMA(a, b, c) __builtin_amdgcn_mfma_f32_32x32x16_bf16((a), (b), (c), 0, 0, 0)
; DI int crow(int r, int h) { return (r & 3) + 8 * (r >> 2) + 4 * h; }
; DI void hg_scan_block(const Params& p, int chain_in, unsigned char* smem) {
;     ...
; #pragma unroll
;     for (int r = 0; r < 16; ++r) {
;       const int pos = 32 * m + crow(r, h), t = dir ? T - 1 - pos : pos;
;       float* dst = OHG + (size_t)(b * SP + soff + t) * 512 + hd * 128 + 32 * sl + l31;
;       *dst = oc[r] + o[r];
;     }
;     const bf16x8 v0 = ld16(s_vT + ((sl * 2 + 0) * 64 + lane) * 8), v1 = ld16(s_vT + ((sl * 2 + 1) * 64 + lane) * 8);
; #pragma unroll
;     for (int k = 0; k < 4; ++k) {
; #pragma unroll
;       for (int g = 0; g < 4; ++g) {
;         const f32x4 d4 = *(const f32x4*)(s_ds + 32 * k + 8 * g + 4 * h);
;         S[k][4 * g] *= d4[0]; S[k][4 * g + 1] *= d4[1]; S[k][4 * g + 2] *= d4[2]; S[k][4 * g + 3] *= d4[3];
;       }
;       S[k] = MFMA(ld16(s_khT + ((k * 2 + 0) * 64 + lane) * 8), v0, S[k]);
;       S[k] = MFMA(ld16(s_khT + ((k * 2 + 1) * 64 + lane) * 8), v1, S[k]);
;     }
; #pragma unroll
;     for (int r = 0; r < 16; ++r) oc[r] = on[r];
	s_nop 0
	v_mfma_f32_32x32x16_bf16 v[64:79], v[150:153], v[154:157], v[64:79]
	s_nop 7
	s_nop 3
	v_add_f32_e32 v64, v148, v64
	v_mad_i32_i24 v162, v161, 0, v160
	global_store_dword v162, v64, s[34:35]
	v_add_f32_e32 v64, v147, v65
	v_mad_i32_i24 v163, v161, 1, v160
	global_store_dword v163, v64, s[34:35]
	v_add_f32_e32 v66, v144, v66
	v_mad_i32_i24 v164, v161, 2, v160
	global_store_dword v164, v66, s[34:35]
	v_add_f32_e32 v66, v142, v67
	v_mad_i32_i24 v165, v161, 3, v160
	global_store_dword v165, v66, s[34:35]
	v_add_f32_e32 v66, v140, v68
	v_mad_i32_i24 v162, v161, 8, v160
	global_store_dword v162, v66, s[34:35]
	v_add_f32_e32 v66, v138, v69
	v_mad_i32_i24 v163, v161, 9, v160
	global_store_dword v163, v66, s[34:35]
	v_add_f32_e32 v66, v137, v70
	v_mad_i32_i24 v164, v161, 10, v160
	global_store_dword v164, v66, s[34:35]
	v_add_f32_e32 v66, v146, v71
	v_mad_i32_i24 v165, v161, 11, v160
	global_store_dword v165, v66, s[34:35]
	v_add_f32_e32 v66, v145, v72
	v_mad_i32_i24 v162, v161, 16, v160
	global_store_dword v162, v66, s[34:35]
	v_add_f32_e32 v66, v143, v73
	v_mad_i32_i24 v163, v161, 17, v160
	global_store_dword v163, v66, s[34:35]
	v_add_f32_e32 v66, v141, v74
	v_mad_i32_i24 v164, v161, 18, v160
	global_store_dword v164, v66, s[34:35]
	v_add_f32_e32 v66, v139, v75
	v_mad_i32_i24 v165, v161, 19, v160
	global_store_dword v165, v66, s[34:35]
	v_add_f32_e32 v66, v136, v76
	v_mad_i32_i24 v162, v161, 24, v160
	global_store_dword v162, v66, s[34:35]
	v_add_f32_e32 v66, v135, v77
	v_mad_i32_i24 v163, v161, 25, v160
	global_store_dword v163, v66, s[34:35]
	v_add_f32_e32 v66, v133, v78
	v_mad_i32_i24 v164, v161, 26, v160
	global_store_dword v164, v66, s[34:35]
	v_not_b32_e32 v65, 27
	v_add_f32_e32 v66, v132, v79
	v_mad_i32_i24 v165, v161, 27, v160
	global_store_dword v165, v66, s[34:35]
	ds_read_b128 v[68:71], v114 offset:16384
	ds_read_b128 v[64:67], v114 offset:17408
	ds_read_b128 v[72:75], v115 offset:24576
	ds_read_b128 v[76:79], v115 offset:24608
	ds_read_b128 v[136:139], v115 offset:24640
	ds_read_b128 v[140:143], v115 offset:24672
	s_mov_b64 s[10:11], 0x200
	s_waitcnt lgkmcnt(0)
	v_pk_mul_f32 v[50:51], v[50:51], v[74:75]
	v_pk_mul_f32 v[48:49], v[48:49], v[72:73]
	ds_read_b128 v[72:75], v113 offset:8192
	v_pk_mul_f32 v[62:63], v[62:63], v[142:143]
	v_pk_mul_f32 v[58:59], v[58:59], v[138:139]
	v_pk_mul_f32 v[54:55], v[54:55], v[78:79]
	v_pk_mul_f32 v[60:61], v[60:61], v[140:141]
	v_pk_mul_f32 v[56:57], v[56:57], v[136:137]
	v_pk_mul_f32 v[52:53], v[52:53], v[76:77]
	v_lshl_add_u64 v[108:109], v[108:109], 0, s[10:11]
	s_waitcnt lgkmcnt(0)
	v_mfma_f32_32x32x16_bf16 v[48:63], v[72:75], v[68:71], v[48:63]
	ds_read_b128 v[72:75], v113 offset:9216
	s_waitcnt lgkmcnt(0)
	v_mfma_f32_32x32x16_bf16 v[48:63], v[72:75], v[64:67], v[48:63]
	ds_read_b128 v[72:75], v115 offset:24704
	ds_read_b128 v[76:79], v115 offset:24736
	ds_read_b128 v[136:139], v115 offset:24768
	ds_read_b128 v[140:143], v115 offset:24800
	s_waitcnt lgkmcnt(3)
	v_pk_mul_f32 v[34:35], v[34:35], v[74:75]
	v_pk_mul_f32 v[32:33], v[32:33], v[72:73]
	ds_read_b128 v[72:75], v113 offset:10240
	s_waitcnt lgkmcnt(1)
	v_pk_mul_f32 v[46:47], v[46:47], v[142:143]
	v_pk_mul_f32 v[42:43], v[42:43], v[138:139]
	v_pk_mul_f32 v[38:39], v[38:39], v[78:79]
	v_pk_mul_f32 v[44:45], v[44:45], v[140:141]
	v_pk_mul_f32 v[40:41], v[40:41], v[136:137]
	v_pk_mul_f32 v[36:37], v[36:37], v[76:77]
	s_waitcnt lgkmcnt(0)
	s_nop 0
	v_mfma_f32_32x32x16_bf16 v[32:47], v[72:75], v[68:71], v[32:47]
	ds_read_b128 v[72:75], v113 offset:11264
	s_waitcnt lgkmcnt(0)
	v_mfma_f32_32x32x16_bf16 v[32:47], v[72:75], v[64:67], v[32:47]
	ds_read_b128 v[72:75], v115 offset:24832
	ds_read_b128 v[76:79], v115 offset:24864
	ds_read_b128 v[136:139], v115 offset:24896
	ds_read_b128 v[140:143], v115 offset:24928
	s_waitcnt lgkmcnt(3)
	v_pk_mul_f32 v[18:19], v[18:19], v[74:75]
	v_pk_mul_f32 v[16:17], v[16:17], v[72:73]
	ds_read_b128 v[72:75], v113 offset:12288
	s_waitcnt lgkmcnt(1)
	v_pk_mul_f32 v[30:31], v[30:31], v[142:143]
	v_pk_mul_f32 v[26:27], v[26:27], v[138:139]
	v_pk_mul_f32 v[22:23], v[22:23], v[78:79]
	v_pk_mul_f32 v[28:29], v[28:29], v[140:141]
	v_pk_mul_f32 v[24:25], v[24:25], v[136:137]
	v_pk_mul_f32 v[20:21], v[20:21], v[76:77]
	s_waitcnt lgkmcnt(0)
	s_nop 0
	v_mfma_f32_32x32x16_bf16 v[16:31], v[72:75], v[68:71], v[16:31]
	ds_read_b128 v[72:75], v113 offset:13312
	s_waitcnt lgkmcnt(0)
	v_mfma_f32_32x32x16_bf16 v[16:31], v[72:75], v[64:67], v[16:31]
	ds_read_b128 v[72:75], v115 offset:24960
	ds_read_b128 v[76:79], v115 offset:24992
	ds_read_b128 v[136:139], v115 offset:25024
	ds_read_b128 v[140:143], v115 offset:25056
	s_waitcnt lgkmcnt(3)
	v_pk_mul_f32 v[2:3], v[2:3], v[74:75]
	v_pk_mul_f32 v[0:1], v[0:1], v[72:73]
	ds_read_b128 v[72:75], v113 offset:14336
	s_waitcnt lgkmcnt(1)
	v_pk_mul_f32 v[14:15], v[14:15], v[142:143]
	v_pk_mul_f32 v[10:11], v[10:11], v[138:139]
	v_pk_mul_f32 v[6:7], v[6:7], v[78:79]
	v_pk_mul_f32 v[12:13], v[12:13], v[140:141]
	v_pk_mul_f32 v[8:9], v[8:9], v[136:137]
	v_pk_mul_f32 v[4:5], v[4:5], v[76:77]
	s_waitcnt lgkmcnt(0)
	v_mfma_f32_32x32x16_bf16 v[0:15], v[72:75], v[68:71], v[0:15]
	ds_read_b128 v[68:71], v113 offset:15360
	s_waitcnt lgkmcnt(0)
	v_mfma_f32_32x32x16_bf16 v[0:15], v[68:71], v[64:67], v[0:15]
	s_waitcnt vmcnt(16)
	v_mov_b32_e32 v132, v134
	v_mov_b32_e32 v133, v131
	v_mov_b32_e32 v135, v130
	v_mov_b32_e32 v145, v125
	v_mov_b32_e32 v146, v124
	v_mov_b32_e32 v144, v119
	v_mov_b32_e32 v147, v118
	v_mov_b32_e32 v148, v117
	v_mov_b32_e32 v136, v129
	v_mov_b32_e32 v139, v128
	v_mov_b32_e32 v141, v127
	v_mov_b32_e32 v143, v126
	v_mov_b32_e32 v137, v123
	v_mov_b32_e32 v138, v122
	v_mov_b32_e32 v140, v121
	v_mov_b32_e32 v142, v120
	v_xor_b32_e32 v113, 0x8000, v113
	v_xor_b32_e32 v114, 0x8000, v114
	v_xor_b32_e32 v115, 0x8000, v115
	v_xor_b32_e32 v116, 0x8000, v116
	s_cbranch_scc0 .LBB0_504

; DI int crow(int r, int h) { return (r & 3) + 8 * (r >> 2) + 4 * h; }
; DI void stream_of(int n, int cpc, int& m, int& T, int& soff) { if (n < cpc) { m = n; T = CTX; soff = 0; } else { m = n - cpc; T = SEQ; soff = CTX; } }
; DI void hg_scan_block(const Params& p, int chain_in, unsigned char* smem) {
;     ...
;     if (n + 1 < 136) {
; #pragma unroll
;       for (int i = 0; i < 6; ++i) st[i] = src[(size_t)(n + 1) * 1536 + tid + 256 * i];
;       dsr = dsg[(size_t)(n + 1) * 128 + (tid & 127)];
;     }
;     float on[16];
;     if (n + 1 < 136) {
;       int m1_, T1_, so1_; stream_of(n + 1, 8, m1_, T1_, so1_);
; #pragma unroll
;       for (int r = 0; r < 16; ++r) {
;         const int pos = 32 * m1_ + crow(r, h), t = dir ? T1_ - 1 - pos : pos;
;         on[r] = OHG[(size_t)(b * SP + so1_ + t) * 512 + hd * 128 + 32 * sl + l31];
;       }
;     } else {
; #pragma unroll
;       for (int r = 0; r < 16; ++r) on[r] = 0.f;
;     }
.LBB0_502:
	s_andn2_b64 vcc, exec, s[10:11]
	s_cbranch_vccnz .LBB0_497
	s_cmp_lt_u32 s21, 7
	s_cselect_b32 s11, 0, -8
	s_cselect_b32 s10, 0x100, s95
	s_cselect_b32 s23, 0, 0x100
	s_add_i32 s11, s11, s21
	s_lshl_b32 s22, s11, 5
	s_add_i32 s22, s22, 32
	s_add_i32 s11, s23, s20
	s_add_i32 s26, s11, s22
	s_sub_i32 s27, s10, s22
	s_add_i32 s27, s27, s11
	s_sub_i32 s27, s27, 32
	s_cmp_lg_u64 s[6:7], 0
	s_cselect_b32 s26, s26, s27
	s_lshl_b32 s26, s26, 11
	s_add_u32 s36, s30, s26
	s_addc_u32 s37, s31, 0
	v_not_b32_e32 v65, 27
	s_branch .LBB0_497
